# panel barriers: returning arrival atomic lets the last arriver skip the poll round trip
# speedup vs baseline: 1.0073x; 1.0025x over previous
; __device__ __forceinline__ unsigned xb_ld(unsigned* p)              { return __hip_atomic_load(p, __ATOMIC_RELAXED, __HIP_MEMORY_SCOPE_AGENT); }
; __device__ __forceinline__ unsigned xb_add(unsigned* p, unsigned v) { return __hip_atomic_fetch_add(p, v, __ATOMIC_RELAXED, __HIP_MEMORY_SCOPE_AGENT); }
; #define XB_SPIN(cond, bar) do { unsigned _sp = 0; while (cond) { __builtin_amdgcn_s_sleep(1); \
;     if ((++_sp & 255u) == 0u) { if (xb_ld(&(bar)[XB_TMO])) break; if (_sp > XB_SPIN_CAP) { atomicAdd(&(bar)[XB_TMO], 1u); break; } } } } while (0)
; #define SEAM(k) do { if (IN(k) && IN((k) + 1)) xcd_barrier(bar); } while (0)
; __device__ __forceinline__ void xcd_barrier(const XcdBarrier& b) {
;     asm volatile("s_waitcnt vmcnt(0)" ::: "memory");
;     __syncthreads();
;     if (threadIdx.x == 0) {
;         unsigned* bar = b.bar;
;         __builtin_amdgcn_s_waitcnt(0);
;         unsigned nloc = b.st[0], nx = b.st[1];
;         if (nloc == 0u) { xcd_barrier_complete(bar, b.x, nloc, nx); b.st[0] = nloc; b.st[1] = nx; }
;         const unsigned old = xb_add(&bar[XB_XSUB(b.x)], 1u);
;         const unsigned gen = old / nloc;
;         if (old + 1u == (gen + 1u) * nloc) {
;             __builtin_amdgcn_fence(__ATOMIC_RELEASE, "agent");
;             asm volatile("s_waitcnt vmcnt(0)" ::: "memory");
;             const unsigned og = xb_add(&bar[XB_TOP], 1u);
;             const unsigned tg = og / nx;
;             if (og + 1u == (tg + 1u) * nx) xb_add(&bar[XB_TOPGEN], 1u);
;             else XB_SPIN(xb_ld(&bar[XB_TOPGEN]) == tg, bar);
;             __builtin_amdgcn_fence(__ATOMIC_ACQUIRE, "agent");
;             xb_add(&bar[XB_XGEN(b.x)], 1u);
;             asm volatile("s_waitcnt vmcnt(0)" ::: "memory");
;         } else {
;             XB_SPIN(xb_ld(&bar[XB_XGEN(b.x)]) == gen, bar);
;             __builtin_amdgcn_fence(__ATOMIC_ACQUIRE, "agent");
;             asm volatile("s_waitcnt vmcnt(0)" ::: "memory");
;         }
;     }
;     __syncthreads();
; }
; __global__ void __launch_bounds__(512, 2) mk_fwd(Args args) {
;     ...
;     SEAM(5);
.Lpb5_fast:
	global_atomic_add v2, v0, v1, s[66:67] sc0
	s_mov_b32 s1, 0
	s_waitcnt vmcnt(0)
	v_readfirstlane_b32 s8, v2
	s_cmp_ge_u32 s8, 3
	s_cbranch_scc1 .Lpb5_done
